# attention: 8 Q loads issued together; counted wait (K only) at chunk-loop top, V waited before first PV MFMA
# speedup vs baseline: 1.0511x; 1.0051x over previous
.LBB0_267:
	s_and_b32 s33, s15, 31
	s_ashr_i32 s36, s15, 5
	s_and_b32 s37, s15, 7
	s_ashr_i32 s40, s15, 3
	s_and_b64 s[16:17], s[0:1], exec
	s_cselect_b32 s16, s37, s36
	s_cselect_b32 s44, s40, s33
	s_ashr_i32 s17, s16, 31
	s_lshl_b64 s[36:37], s[16:17], 11
	s_lshl_b32 s17, s44, 6
	s_ashr_i32 s33, s17, 31
	s_add_u32 s17, s36, s17
	v_or_b32_e32 v176, s17, v164
	v_mov_b64_e32 v[6:7], s[62:63]
	s_movk_i32 s40, 0xc00
	s_addc_u32 s33, s37, s33
	v_mad_u64_u32 v[2:3], s[36:37], v176, s40, v[6:7]
	v_mad_i32_i24 v3, s33, v225, v3
	v_lshl_add_u64 v[2:3], v[2:3], 0, v[172:173]
	v_mov_b32_e32 v169, v196
	v_lshl_add_u64 v[2:3], v[2:3], 0, v[168:169]
	s_mov_b64 s[18:19], 0x3f80800
	s_mov_b32 s41, 0x3f80000
	v_lshl_add_u64 v[8:9], v[2:3], 0, s[18:19]
	v_add_co_u32_e32 v2, vcc, s41, v2
	v_or_b32_e32 v174, s17, v166
	s_nop 0
	v_addc_co_u32_e32 v3, vcc, 0, v3, vcc
	global_load_dwordx4 v[98:101], v[2:3], off offset:2048
	s_sub_i32 s17, 8, s44
	s_cmp_lt_i32 s44, 8
	v_mov_b32_e32 v177, s33
	v_mov_b32_e32 v175, s33
	global_load_dwordx4 v[102:105], v[8:9], off offset:32
	global_load_dwordx4 v[106:109], v[8:9], off offset:64
	global_load_dwordx4 v[110:113], v[8:9], off offset:96
	v_mad_u64_u32 v[2:3], s[36:37], v174, s40, v[6:7]
	v_mad_i32_i24 v3, s33, v225, v3
	v_lshl_add_u64 v[2:3], v[2:3], 0, v[172:173]
	v_lshl_add_u64 v[2:3], v[2:3], 0, v[168:169]
	v_lshl_add_u64 v[6:7], v[2:3], 0, s[18:19]
	v_add_co_u32_e32 v2, vcc, s41, v2
	s_cselect_b32 s33, s17, 0
	s_nop 0
	v_addc_co_u32_e32 v3, vcc, 0, v3, vcc
	global_load_dwordx4 v[114:117], v[2:3], off offset:2048
	v_readfirstlane_b32 s17, v163
	s_mov_b64 s[36:37], -1
	s_cmp_lt_i32 s33, 9
	global_load_dwordx4 v[118:121], v[6:7], off offset:32
	global_load_dwordx4 v[122:125], v[6:7], off offset:64
	global_load_dwordx4 v[126:129], v[6:7], off offset:96
	s_waitcnt vmcnt(7)
	ds_write_b128 v167, v[98:101] offset:16384
	s_waitcnt vmcnt(6)
	ds_write_b128 v167, v[102:105] offset:17408
	s_waitcnt vmcnt(5)
	ds_write_b128 v167, v[106:109] offset:18432
	s_waitcnt vmcnt(4)
	ds_write_b128 v167, v[110:113] offset:19456
	s_waitcnt vmcnt(3)
	ds_write_b128 v167, v[114:117] offset:20480
	s_waitcnt vmcnt(2)
	ds_write_b128 v167, v[118:121] offset:21504
	s_waitcnt vmcnt(1)
	ds_write_b128 v167, v[122:125] offset:22528
	s_waitcnt vmcnt(0)
	ds_write_b128 v167, v[126:129] offset:23552
	s_cbranch_scc1 .LBB0_269
	v_mbcnt_hi_u32_b32 v4, -1, v252
	v_and_b32_e32 v2, 64, v4
	v_xor_b32_e32 v198, 32, v4
	v_add_u32_e32 v230, 64, v2
	s_mov_b64 s[36:37], 0
.LBB0_269:
	v_mov_b32_e32 v97, 0
	s_andn2_b64 vcc, exec, s[36:37]
	v_mov_b32_e32 v96, v97
	v_mov_b32_e32 v95, v97
	v_mov_b32_e32 v94, v97
	v_mov_b32_e32 v93, v97
	v_mov_b32_e32 v92, v97
	v_mov_b32_e32 v91, v97
	v_mov_b32_e32 v90, v97
	v_mov_b32_e32 v89, v97
	v_mov_b32_e32 v88, v97
	v_mov_b32_e32 v87, v97
	v_mov_b32_e32 v86, v97
	v_mov_b32_e32 v85, v97
	v_mov_b32_e32 v84, v97
	v_mov_b32_e32 v83, v97
	v_mov_b32_e32 v82, v97
	v_mov_b32_e32 v81, v97
	v_mov_b32_e32 v80, v97
	v_mov_b32_e32 v79, v97
	v_mov_b32_e32 v78, v97
	v_mov_b32_e32 v77, v97
	v_mov_b32_e32 v76, v97
	v_mov_b32_e32 v75, v97
	v_mov_b32_e32 v74, v97
	v_mov_b32_e32 v73, v97
	v_mov_b32_e32 v72, v97
	v_mov_b32_e32 v71, v97
	v_mov_b32_e32 v70, v97
	v_mov_b32_e32 v69, v97
	v_mov_b32_e32 v68, v97
	v_mov_b32_e32 v67, v97
	v_mov_b32_e32 v66, v97
	v_mov_b32_e32 v65, v97
	v_mov_b32_e32 v64, v97
	v_mov_b32_e32 v63, v97
	v_mov_b32_e32 v62, v97
	v_mov_b32_e32 v61, v97
	v_mov_b32_e32 v60, v97
	v_mov_b32_e32 v59, v97
	v_mov_b32_e32 v58, v97
	v_mov_b32_e32 v57, v97
	v_mov_b32_e32 v56, v97
	v_mov_b32_e32 v55, v97
	v_mov_b32_e32 v54, v97
	v_mov_b32_e32 v53, v97
	v_mov_b32_e32 v52, v97
	v_mov_b32_e32 v51, v97
	v_mov_b32_e32 v50, v97
	v_mov_b32_e32 v49, v97
	v_mov_b32_e32 v48, v97
	v_mov_b32_e32 v47, v97
	v_mov_b32_e32 v46, v97
	v_mov_b32_e32 v45, v97
	v_mov_b32_e32 v44, v97
	v_mov_b32_e32 v43, v97
	v_mov_b32_e32 v42, v97
	v_mov_b32_e32 v41, v97
	v_mov_b32_e32 v40, v97
	v_mov_b32_e32 v39, v97
	v_mov_b32_e32 v38, v97
	v_mov_b32_e32 v37, v97
	v_mov_b32_e32 v36, v97
	v_mov_b32_e32 v35, v97
	v_mov_b32_e32 v34, v97
	v_mov_b32_e32 v3, v97
	v_mov_b32_e32 v2, v97
	s_cbranch_vccnz .LBB0_266
	s_lshl_b32 s16, s16, 3
	s_add_i32 s16, s17, s16
	s_ashr_i32 s17, s16, 31
	s_lshl_b64 s[16:17], s[16:17], 18
	v_readlane_b32 s18, v255, 41
	v_readlane_b32 s19, v255, 42
	s_add_u32 s40, s18, s16
	s_addc_u32 s41, s19, s17
	v_readlane_b32 s18, v255, 39
	v_readlane_b32 s19, v255, 40
	s_add_u32 s42, s18, s16
	s_addc_u32 s43, s19, s17
	s_add_i32 s16, s33, s44
	s_lshl_b32 s36, s16, 12
	s_add_i32 s16, s36, 0xffff8000
	v_mov_b32_e32 v171, v196
	s_ashr_i32 s17, s16, 31
	v_lshl_add_u64 v[2:3], s[42:43], 0, v[170:171]
	s_lshl_b64 s[16:17], s[16:17], 1
	v_lshl_add_u64 v[2:3], v[2:3], 0, s[16:17]
	s_movk_i32 s37, 0x1000
	v_add_co_u32_e32 v4, vcc, s37, v2
	s_add_i32 s44, s36, 0xffff9000
	s_nop 0
	v_addc_co_u32_e32 v5, vcc, 0, v3, vcc
	global_load_dwordx4 v[138:141], v[4:5], off offset:3072
	global_load_dwordx4 v[98:101], v[4:5], off offset:2048
	global_load_dwordx4 v[142:145], v[4:5], off offset:1024
	global_load_dwordx4 v[102:105], v[4:5], off
	global_load_dwordx4 v[106:109], v[2:3], off offset:3072
	global_load_dwordx4 v[114:117], v[2:3], off offset:2048
	global_load_dwordx4 v[110:113], v[2:3], off offset:1024
	global_load_dwordx4 v[118:121], v[2:3], off
	v_lshl_add_u64 v[2:3], s[40:41], 0, v[170:171]
	v_lshl_add_u64 v[2:3], v[2:3], 0, s[16:17]
	v_add_co_u32_e32 v4, vcc, s37, v2
	s_lshl_b32 s16, s33, 6
	s_nop 0
	v_addc_co_u32_e32 v5, vcc, 0, v3, vcc
	global_load_dwordx4 v[154:157], v[4:5], off offset:3072
	global_load_dwordx4 v[158:161], v[4:5], off offset:2048
	global_load_dwordx4 v[146:149], v[4:5], off offset:1024
	global_load_dwordx4 v[150:153], v[4:5], off
	global_load_dwordx4 v[122:125], v[2:3], off offset:3072
	global_load_dwordx4 v[126:129], v[2:3], off offset:2048
	global_load_dwordx4 v[130:133], v[2:3], off offset:1024
	global_load_dwordx4 v[134:137], v[2:3], off
	v_mov_b32_e32 v171, 0
	s_sub_i32 s70, 0x2a0, s16
	v_mov_b32_e32 v197, 0xff800000
	v_mov_b32_e32 v221, 0xff800000
	v_mov_b32_e32 v169, 0
	v_mov_b32_e32 v34, 0
	v_mov_b32_e32 v35, v171
	v_mov_b32_e32 v36, v171
	v_mov_b32_e32 v37, v171
	v_mov_b32_e32 v38, v171
	v_mov_b32_e32 v39, v171
	v_mov_b32_e32 v40, v171
	v_mov_b32_e32 v41, v171
	v_mov_b32_e32 v42, v171
	v_mov_b32_e32 v43, v171
	v_mov_b32_e32 v44, v171
	v_mov_b32_e32 v45, v171
	v_mov_b32_e32 v46, v171
	v_mov_b32_e32 v47, v171
	v_mov_b32_e32 v48, v171
	v_mov_b32_e32 v49, v171
	v_mov_b32_e32 v50, 0
	v_mov_b32_e32 v51, v171
	v_mov_b32_e32 v52, v171
	v_mov_b32_e32 v53, v171
	v_mov_b32_e32 v54, v171
	v_mov_b32_e32 v55, v171
	v_mov_b32_e32 v56, v171
	v_mov_b32_e32 v57, v171
	v_mov_b32_e32 v58, v171
	v_mov_b32_e32 v59, v171
	v_mov_b32_e32 v60, v171
	v_mov_b32_e32 v61, v171
	v_mov_b32_e32 v62, v171
	v_mov_b32_e32 v63, v171
	v_mov_b32_e32 v64, v171
	v_mov_b32_e32 v65, v171
	v_mov_b32_e32 v66, 0
	v_mov_b32_e32 v67, v171
	v_mov_b32_e32 v68, v171
	v_mov_b32_e32 v69, v171
	v_mov_b32_e32 v70, v171
	v_mov_b32_e32 v71, v171
	v_mov_b32_e32 v72, v171
	v_mov_b32_e32 v73, v171
	v_mov_b32_e32 v74, v171
	v_mov_b32_e32 v75, v171
	v_mov_b32_e32 v76, v171
	v_mov_b32_e32 v77, v171
	v_mov_b32_e32 v78, v171
	v_mov_b32_e32 v79, v171
	v_mov_b32_e32 v80, v171
	v_mov_b32_e32 v81, v171
	v_mov_b32_e32 v82, 0
	v_mov_b32_e32 v83, v171
	v_mov_b32_e32 v84, v171
	v_mov_b32_e32 v85, v171
	v_mov_b32_e32 v86, v171
	v_mov_b32_e32 v87, v171
	v_mov_b32_e32 v88, v171
	v_mov_b32_e32 v89, v171
	v_mov_b32_e32 v90, v171
	v_mov_b32_e32 v91, v171
	v_mov_b32_e32 v92, v171
	v_mov_b32_e32 v93, v171
	v_mov_b32_e32 v94, v171
	v_mov_b32_e32 v95, v171
	v_mov_b32_e32 v96, v171
	v_mov_b32_e32 v97, v171
	s_waitcnt vmcnt(0)
.LBB0_271:
	v_mov_b32 v2, v0
	s_cmp_gt_i32 s33, 5
	v_and_b32_e32 v3, 31, v2
	v_and_b32_e32 v246, 63, v2
	v_lshlrev_b32_e32 v4, 7, v2
	v_lshrrev_b32_e32 v2, 3, v2
	v_and_b32_e32 v2, 4, v2
	v_and_b32_e32 v4, 0xffffe000, v4
	v_sub_u32_e32 v2, v3, v2
	v_add_u32_e32 v4, 0, v4
	v_lshlrev_b32_e32 v5, 4, v246
	v_add_u32_e32 v231, s70, v2
	s_cselect_b64 s[16:17], -1, 0
	v_add_u32_e32 v245, v4, v5
	v_subrev_u32_e32 v190, 32, v231
	ds_read_b128 v[2:5], v245 offset:16384
	ds_read_b128 v[178:181], v245 offset:17408
	ds_read_b128 v[182:185], v245 offset:18432
	ds_read_b128 v[186:189], v245 offset:19456
	v_subrev_u32_e32 v191, 57, v231
	s_waitcnt vmcnt(8) lgkmcnt(3)
	v_mfma_f32_32x32x16_bf16 v[18:33], v[134:137], v[2:5], 0
	v_subrev_u32_e32 v192, 58, v231
	v_subrev_u32_e32 v193, 59, v231
	s_mov_b64 s[36:37], -1
	s_and_b64 vcc, exec, s[16:17]
	v_min_i32_e32 v232, 0x100, v191
	v_min_i32_e32 v223, 0x100, v192
	v_min_i32_e32 v222, 0x100, v193
	v_mfma_f32_32x32x16_bf16 v[2:17], v[150:153], v[2:5], 0
	s_waitcnt lgkmcnt(2)
	v_mfma_f32_32x32x16_bf16 v[18:33], v[130:133], v[178:181], v[18:33]
	v_mfma_f32_32x32x16_bf16 v[2:17], v[146:149], v[178:181], v[2:17]
	v_min_i32_e32 v178, 0x100, v190
	v_subrev_u32_e32 v179, 33, v231
	v_subrev_u32_e32 v180, 34, v231
	v_subrev_u32_e32 v181, 35, v231
	v_subrev_u32_e32 v190, 56, v231
	v_lshl_add_u32 v220, v178, 2, v162
	v_min_i32_e32 v244, 0x100, v179
	s_waitcnt lgkmcnt(1)
	v_mfma_f32_32x32x16_bf16 v[18:33], v[126:129], v[182:185], v[18:33]
	v_min_i32_e32 v243, 0x100, v180
	v_min_i32_e32 v242, 0x100, v181
	v_min_i32_e32 v233, 0x100, v190
	v_mfma_f32_32x32x16_bf16 v[2:17], v[158:161], v[182:185], v[2:17]
	v_subrev_u32_e32 v182, 40, v231
	v_subrev_u32_e32 v183, 41, v231
	v_subrev_u32_e32 v184, 42, v231
	v_subrev_u32_e32 v185, 43, v231
	v_min_i32_e32 v241, 0x100, v182
	v_min_i32_e32 v240, 0x100, v183
	v_min_i32_e32 v239, 0x100, v184
	s_waitcnt lgkmcnt(0)
	v_mfma_f32_32x32x16_bf16 v[18:33], v[122:125], v[186:189], v[18:33]
	v_min_i32_e32 v238, 0x100, v185
	v_mfma_f32_32x32x16_bf16 v[2:17], v[154:157], v[186:189], v[2:17]
	v_subrev_u32_e32 v186, 48, v231
	v_subrev_u32_e32 v187, 49, v231
	v_subrev_u32_e32 v188, 50, v231
	v_subrev_u32_e32 v189, 51, v231
	v_min_i32_e32 v237, 0x100, v186
	v_min_i32_e32 v236, 0x100, v187
	v_min_i32_e32 v235, 0x100, v188
	v_min_i32_e32 v234, 0x100, v189
	s_cbranch_vccz .LBB0_273
	v_lshl_add_u32 v178, v244, 2, v162
	v_lshl_add_u32 v180, v243, 2, v162
	v_lshl_add_u32 v181, v242, 2, v162
	v_lshl_add_u32 v182, v241, 2, v162
	v_lshl_add_u32 v183, v240, 2, v162
	v_lshl_add_u32 v184, v239, 2, v162
	v_lshl_add_u32 v185, v238, 2, v162
	v_lshl_add_u32 v186, v237, 2, v162
	ds_read_b32 v179, v178
	ds_read_b32 v180, v180
	ds_read_b32 v181, v181
	ds_read_b32 v182, v182
	ds_read_b32 v183, v183
	ds_read_b32 v184, v184
	ds_read_b32 v185, v185
	ds_read_b32 v186, v186
	v_add_u32_e32 v178, 0xffffffaf, v231
	v_min_i32_e32 v178, 0x100, v178
	v_lshl_add_u32 v187, v178, 2, v162
	v_add_u32_e32 v178, 0xffffffae, v231
	v_min_i32_e32 v178, 0x100, v178
	v_lshl_add_u32 v188, v178, 2, v162
	v_add_u32_e32 v178, 0xffffffad, v231
	v_min_i32_e32 v178, 0x100, v178
	v_lshl_add_u32 v190, v178, 2, v162
	v_add_u32_e32 v178, 0xffffffa8, v231
	v_min_i32_e32 v178, 0x100, v178
	v_lshl_add_u32 v191, v178, 2, v162
	v_add_u32_e32 v178, 0xffffffa7, v231
	v_min_i32_e32 v178, 0x100, v178
	v_lshl_add_u32 v192, v178, 2, v162
	v_add_u32_e32 v178, 0xffffffa6, v231
	v_min_i32_e32 v178, 0x100, v178
	v_lshl_add_u32 v193, v178, 2, v162
	v_add_u32_e32 v178, 0xffffffa5, v231
	v_min_i32_e32 v178, 0x100, v178
	v_lshl_add_u32 v194, v178, 2, v162
	ds_read_b32 v178, v220
	ds_read_b32 v189, v187
	ds_read_b32 v198, v188
	ds_read_b32 v199, v190
	ds_read_b32 v200, v191
	ds_read_b32 v201, v192
	ds_read_b32 v226, v193
	ds_read_b32 v227, v194
	s_waitcnt lgkmcnt(7)
	v_pk_fma_f32 v[218:219], v[18:19], s[12:13], v[178:179] op_sel_hi:[1,0,1]
	v_pk_fma_f32 v[216:217], v[20:21], s[12:13], v[180:181] op_sel_hi:[1,0,1]
	v_max3_f32 v178, v218, s13, v219
	v_max3_f32 v178, v178, v216, v217
	v_pk_fma_f32 v[214:215], v[22:23], s[12:13], v[182:183] op_sel_hi:[1,0,1]
	v_pk_fma_f32 v[208:209], v[24:25], s[12:13], v[184:185] op_sel_hi:[1,0,1]
	v_max3_f32 v178, v178, v214, v215
	v_subrev_u32_e32 v187, 64, v231
	v_max3_f32 v185, v178, v208, v209
	v_lshl_add_u32 v178, v236, 2, v162
	v_lshl_add_u32 v179, v235, 2, v162
	v_lshl_add_u32 v180, v234, 2, v162
	v_lshl_add_u32 v181, v233, 2, v162
	v_lshl_add_u32 v182, v232, 2, v162
	v_lshl_add_u32 v183, v223, 2, v162
	v_lshl_add_u32 v184, v222, 2, v162
	v_min_i32_e32 v187, 0x100, v187
	v_lshl_add_u32 v188, v187, 2, v162
	ds_read_b32 v187, v178
	ds_read_b32 v178, v179
	ds_read_b32 v179, v180
	ds_read_b32 v180, v181
	ds_read_b32 v181, v182
	ds_read_b32 v182, v183
	ds_read_b32 v183, v184
	ds_read_b32 v184, v188
	s_waitcnt lgkmcnt(7)
	v_pk_fma_f32 v[212:213], v[26:27], s[12:13], v[186:187] op_sel_hi:[1,0,1]
	s_waitcnt lgkmcnt(5)
	v_pk_fma_f32 v[206:207], v[28:29], s[12:13], v[178:179] op_sel_hi:[1,0,1]
	v_max3_f32 v185, v185, v212, v213
	v_max3_f32 v178, v185, v206, v207
	s_waitcnt lgkmcnt(3)
	v_pk_fma_f32 v[202:203], v[30:31], s[12:13], v[180:181] op_sel_hi:[1,0,1]
	v_add_u32_e32 v185, 0xffffffb5, v231
	v_max3_f32 v178, v178, v202, v203
	s_waitcnt lgkmcnt(1)
	v_pk_fma_f32 v[192:193], v[32:33], s[12:13], v[182:183] op_sel_hi:[1,0,1]
	v_min_i32_e32 v185, 0x100, v185
	v_max3_f32 v186, v178, v192, v193
	v_add_u32_e32 v178, 0xffffffbf, v231
	v_add_u32_e32 v179, 0xffffffbe, v231
	v_add_u32_e32 v180, 0xffffffbd, v231
	v_add_u32_e32 v181, 0xffffffb8, v231
	v_add_u32_e32 v182, 0xffffffb7, v231
	v_add_u32_e32 v183, 0xffffffb6, v231
	v_lshl_add_u32 v187, v185, 2, v162
	v_add_u32_e32 v185, 0xffffffb0, v231
	v_min_i32_e32 v178, 0x100, v178
	v_min_i32_e32 v179, 0x100, v179
	v_min_i32_e32 v180, 0x100, v180
	v_min_i32_e32 v181, 0x100, v181
	v_min_i32_e32 v182, 0x100, v182
	v_min_i32_e32 v183, 0x100, v183
	v_min_i32_e32 v185, 0x100, v185
	v_lshl_add_u32 v178, v178, 2, v162
	v_lshl_add_u32 v179, v179, 2, v162
	v_lshl_add_u32 v180, v180, 2, v162
	v_lshl_add_u32 v181, v181, 2, v162
	v_lshl_add_u32 v182, v182, 2, v162
	v_lshl_add_u32 v183, v183, 2, v162
	v_lshl_add_u32 v188, v185, 2, v162
	ds_read_b32 v185, v178
	ds_read_b32 v178, v179
	ds_read_b32 v179, v180
	ds_read_b32 v180, v181
	ds_read_b32 v181, v182
	ds_read_b32 v182, v183
	ds_read_b32 v183, v187
	ds_read_b32 v188, v188
	s_waitcnt lgkmcnt(7)
	v_pk_fma_f32 v[210:211], v[2:3], s[12:13], v[184:185] op_sel_hi:[1,0,1]
	s_waitcnt lgkmcnt(5)
	v_pk_fma_f32 v[204:205], v[4:5], s[12:13], v[178:179] op_sel_hi:[1,0,1]
	v_max3_f32 v184, v186, v210, v211
	v_max3_f32 v178, v184, v204, v205
	s_waitcnt lgkmcnt(3)
	v_pk_fma_f32 v[194:195], v[6:7], s[12:13], v[180:181] op_sel_hi:[1,0,1]
	s_waitcnt lgkmcnt(1)
	v_pk_fma_f32 v[190:191], v[8:9], s[12:13], v[182:183] op_sel_hi:[1,0,1]
	v_max3_f32 v178, v178, v194, v195
	v_max3_f32 v178, v178, v190, v191
	s_waitcnt lgkmcnt(0)
	v_pk_fma_f32 v[188:189], v[10:11], s[12:13], v[188:189] op_sel_hi:[1,0,1]
	v_pk_fma_f32 v[186:187], v[12:13], s[12:13], v[198:199] op_sel_hi:[1,0,1]
	v_max3_f32 v178, v178, v188, v189
	v_max3_f32 v178, v178, v186, v187
	v_pk_fma_f32 v[184:185], v[14:15], s[12:13], v[200:201] op_sel_hi:[1,0,1]
	v_pk_fma_f32 v[182:183], v[16:17], s[12:13], v[226:227] op_sel_hi:[1,0,1]
	v_max3_f32 v178, v178, v184, v185
	v_max3_f32 v178, v178, v182, v183
	s_mov_b64 s[36:37], 0

.LBB0_279:
	v_sub_f32_e32 v33, v221, v179
	v_exp_f32_e32 v178, v33
	v_cvt_pk_bf16_f32 v2, v2, v3
	v_cvt_pk_bf16_f32 v3, v4, v5
	v_cvt_pk_bf16_f32 v4, v6, v7
	v_cvt_pk_bf16_f32 v5, v8, v9
	v_exp_f32_e32 v181, v181
	v_pk_mul_f32 v[96:97], v[96:97], v[178:179] op_sel_hi:[1,0]
	v_pk_mul_f32 v[94:95], v[94:95], v[178:179] op_sel_hi:[1,0]
	v_pk_mul_f32 v[92:93], v[92:93], v[178:179] op_sel_hi:[1,0]
	v_pk_mul_f32 v[90:91], v[90:91], v[178:179] op_sel_hi:[1,0]
	v_pk_mul_f32 v[88:89], v[88:89], v[178:179] op_sel_hi:[1,0]
	v_pk_mul_f32 v[86:87], v[86:87], v[178:179] op_sel_hi:[1,0]
	v_pk_mul_f32 v[84:85], v[84:85], v[178:179] op_sel_hi:[1,0]
	v_pk_mul_f32 v[82:83], v[82:83], v[178:179] op_sel_hi:[1,0]
	v_pk_mul_f32 v[80:81], v[80:81], v[178:179] op_sel_hi:[1,0]
	v_pk_mul_f32 v[78:79], v[78:79], v[178:179] op_sel_hi:[1,0]
	v_pk_mul_f32 v[76:77], v[76:77], v[178:179] op_sel_hi:[1,0]
	v_pk_mul_f32 v[74:75], v[74:75], v[178:179] op_sel_hi:[1,0]
	v_pk_mul_f32 v[72:73], v[72:73], v[178:179] op_sel_hi:[1,0]
	v_pk_mul_f32 v[70:71], v[70:71], v[178:179] op_sel_hi:[1,0]
	v_pk_mul_f32 v[68:69], v[68:69], v[178:179] op_sel_hi:[1,0]
	v_pk_mul_f32 v[66:67], v[66:67], v[178:179] op_sel_hi:[1,0]
	s_waitcnt vmcnt(0)
	v_mfma_f32_32x32x16_bf16 v[82:97], v[118:121], v[2:5], v[82:97]
	s_cmp_lg_u32 s33, 8
	s_cselect_b64 s[16:17], -1, 0
	v_lshlrev_b32_e32 v194, 3, v246
	s_cmp_eq_u32 s33, 8
	v_mfma_f32_32x32x16_bf16 v[66:81], v[110:113], v[2:5], v[66:81]
	v_cvt_pk_bf16_f32 v2, v10, v11
	v_cvt_pk_bf16_f32 v3, v12, v13
	v_cvt_pk_bf16_f32 v4, v14, v15
	v_cvt_pk_bf16_f32 v5, v16, v17
	s_nop 0
	v_mfma_f32_32x32x16_bf16 v[82:97], v[114:117], v[2:5], v[82:97]
	v_mfma_f32_32x32x16_bf16 v[66:81], v[106:109], v[2:5], v[66:81]
	v_cvt_pk_bf16_f32 v2, v18, v19
	v_cvt_pk_bf16_f32 v3, v20, v21
	v_cvt_pk_bf16_f32 v4, v22, v23
	v_cvt_pk_bf16_f32 v5, v24, v25
	s_nop 0
	v_mfma_f32_32x32x16_bf16 v[82:97], v[102:105], v[2:5], v[82:97]
	v_mfma_f32_32x32x16_bf16 v[66:81], v[142:145], v[2:5], v[66:81]
	v_cvt_pk_bf16_f32 v2, v26, v27
	v_cvt_pk_bf16_f32 v3, v28, v29
	v_cvt_pk_bf16_f32 v4, v30, v31
	v_cvt_pk_bf16_f32 v5, v32, v181
	s_nop 0
	v_mfma_f32_32x32x16_bf16 v[82:97], v[98:101], v[2:5], v[82:97]
	v_mfma_f32_32x32x16_bf16 v[66:81], v[138:141], v[2:5], v[66:81]
	ds_read_b128 v[2:5], v245 offset:20480
	ds_read_b128 v[182:185], v245 offset:21504
	ds_read_b128 v[186:189], v245 offset:22528
	ds_read_b128 v[190:193], v245 offset:23552
	s_waitcnt lgkmcnt(3)
	v_mfma_f32_32x32x16_bf16 v[18:33], v[134:137], v[2:5], 0
	v_mfma_f32_32x32x16_bf16 v[2:17], v[150:153], v[2:5], 0
	s_waitcnt lgkmcnt(2)
	v_mfma_f32_32x32x16_bf16 v[18:33], v[130:133], v[182:185], v[18:33]
	v_mfma_f32_32x32x16_bf16 v[2:17], v[146:149], v[182:185], v[2:17]
	v_lshlrev_b32_e32 v182, 1, v194
	s_waitcnt lgkmcnt(1)
	v_mfma_f32_32x32x16_bf16 v[18:33], v[126:129], v[186:189], v[18:33]
	v_mfma_f32_32x32x16_bf16 v[2:17], v[158:161], v[186:189], v[2:17]
	s_waitcnt lgkmcnt(0)
	v_mfma_f32_32x32x16_bf16 v[18:33], v[122:125], v[190:193], v[18:33]
	v_mfma_f32_32x32x16_bf16 v[2:17], v[154:157], v[190:193], v[2:17]
	s_cbranch_scc1 .LBB0_281
	v_mov_b32_e32 v183, v196
	v_lshl_add_u64 v[154:155], s[40:41], 0, v[182:183]
	s_add_i32 s68, s44, 0x800
	s_mov_b32 s69, s46
	s_mov_b32 s45, s46
	v_lshl_add_u64 v[146:147], s[68:69], 1, v[154:155]
	s_add_i32 s68, s44, 0xa00
	v_lshl_add_u64 v[122:123], s[44:45], 1, v[154:155]
	v_lshl_add_u64 v[148:149], s[68:69], 1, v[154:155]
	s_add_i32 s68, s44, 0xc00
	global_load_dwordx4 v[134:137], v[122:123], off
	global_load_dwordx4 v[130:133], v[122:123], off offset:1024
	global_load_dwordx4 v[126:129], v[122:123], off offset:2048
	s_nop 0
	global_load_dwordx4 v[122:125], v[122:123], off offset:3072
	v_lshl_add_u64 v[156:157], s[68:69], 1, v[154:155]
	s_add_i32 s68, s44, 0xe00
	v_lshl_add_u64 v[154:155], s[68:69], 1, v[154:155]
	global_load_dwordx4 v[150:153], v[146:147], off
	s_nop 0
	global_load_dwordx4 v[146:149], v[148:149], off
	s_nop 0
	global_load_dwordx4 v[158:161], v[156:157], off
	s_nop 0
	global_load_dwordx4 v[154:157], v[154:155], off
